# cache-policy hints: nt on streaming f32 residual-stream loads/stores and y loads in resid16, x loads in P1 rowstat
# speedup vs baseline: 1.0161x; 1.0105x over previous
.LBB0_27:
	v_mov_b32_e32 v1, v0
	s_add_i32 s4, s0, s1
	s_waitcnt vmcnt(0)
	v_ashrrev_i32_e32 v2, 6, v1
	v_add_u32_e32 v4, s4, v2
	v_add_u32_e32 v2, 0xfffff800, v4
	v_cmp_gt_i32_e32 vcc, s5, v2
	v_ashrrev_i32_e32 v3, 31, v2
	v_add_u32_e32 v4, 0xffffb800, v4
	v_mov_b32_e32 v6, s41
	v_mov_b32_e32 v7, s37
	v_cndmask_b32_e32 v5, 0, v3, vcc
	v_cndmask_b32_e32 v4, v4, v2, vcc
	v_cndmask_b32_e32 v7, v6, v7, vcc
	v_mov_b32_e32 v6, s40
	v_mov_b32_e32 v8, s36
	v_lshlrev_b32_e32 v1, 2, v1
	v_cndmask_b32_e32 v6, v6, v8, vcc
	v_lshlrev_b64 v[4:5], 12, v[4:5]
	v_and_b32_e32 v1, 0xfc, v1
	v_lshl_add_u64 v[4:5], v[6:7], 0, v[4:5]
	v_lshlrev_b32_e32 v130, 2, v1
	v_cmp_lt_i32_e32 vcc, v201, v200
	v_lshl_add_u64 v[18:19], v[4:5], 0, v[130:131]
	s_add_i32 s1, s1, 4
	v_cndmask_b32_e32 v4, v198, v201, vcc
	v_cmp_lt_i32_e32 vcc, v202, v200
	v_lshlrev_b32_e32 v42, 2, v4
	s_cmp_lg_u32 s1, 16
	v_cndmask_b32_e32 v4, v198, v202, vcc
	v_cmp_lt_i32_e32 vcc, v203, v200
	v_lshlrev_b32_e32 v43, 2, v4
	s_nop 0
	v_cndmask_b32_e32 v4, v198, v203, vcc
	v_cmp_lt_i32_e32 vcc, v204, v200
	v_lshlrev_b32_e32 v44, 2, v4
	s_nop 0
	v_cndmask_b32_e32 v4, v198, v204, vcc
	v_cmp_lt_i32_e32 vcc, v205, v200
	v_lshlrev_b32_e32 v45, 2, v4
	s_nop 0
	v_cndmask_b32_e32 v4, v198, v205, vcc
	v_cmp_lt_i32_e32 vcc, v206, v200
	v_lshlrev_b32_e32 v46, 2, v4
	s_nop 0
	v_cndmask_b32_e32 v4, v198, v206, vcc
	v_lshlrev_b32_e32 v47, 2, v4
	v_min_i32_e32 v4, 0x4000, v2
	v_ashrrev_i32_e32 v4, 12, v4
	v_mul_i32_i24_e32 v4, 0xc00, v4
	v_ashrrev_i32_e32 v5, 31, v4
	v_lshl_add_u64 v[4:5], v[4:5], 2, s[6:7]
	v_lshl_add_u64 v[28:29], v[4:5], 0, v[130:131]
	v_lshlrev_b64 v[2:3], 11, v[2:3]
	v_add_co_u32_e32 v30, vcc, s8, v28
	v_lshl_add_u64 v[2:3], s[94:95], 0, v[2:3]
	v_lshlrev_b32_e32 v130, 1, v1
	v_addc_co_u32_e32 v31, vcc, 0, v29, vcc
	v_lshl_add_u64 v[26:27], v[2:3], 0, v[130:131]
	global_load_dwordx4 v[14:17], v[18:19], off nt
	global_load_dwordx4 v[2:5], v[28:29], off
	global_load_dwordx4 v[10:13], v[30:31], off
	global_load_dwordx4 v[6:9], v[18:19], off offset:1024 nt
	s_waitcnt vmcnt(3)
	v_mov_b32_e32 v32, v15
	v_mov_b32_e32 v24, v14
	s_waitcnt vmcnt(0)
	v_mov_b32_e32 v33, v7
	v_mov_b32_e32 v25, v6
	v_pk_mul_f32 v[32:33], v[32:33], v[32:33]
	v_mov_b32_e32 v20, v16
	v_mov_b32_e32 v21, v8
	v_pk_fma_f32 v[24:25], v[24:25], v[24:25], v[32:33]
	v_mov_b32_e32 v22, v17
	v_mov_b32_e32 v23, v9
	v_pk_fma_f32 v[20:21], v[20:21], v[20:21], v[24:25]
	s_nop 0
	v_pk_fma_f32 v[32:33], v[22:23], v[22:23], v[20:21]
	global_load_dwordx4 v[22:25], v[18:19], off offset:2048 nt
	s_nop 0
	global_load_dwordx4 v[18:21], v[18:19], off offset:3072 nt
	v_add_f32_e32 v1, v32, v33
	s_waitcnt vmcnt(1)
	v_mov_b32_e32 v40, v23
	s_waitcnt vmcnt(0)
	v_mov_b32_e32 v41, v19
	v_mov_b32_e32 v38, v22
	v_mov_b32_e32 v39, v18
	v_pk_mul_f32 v[40:41], v[40:41], v[40:41]
	v_mov_b32_e32 v34, v24
	v_mov_b32_e32 v35, v20
	v_pk_fma_f32 v[38:39], v[38:39], v[38:39], v[40:41]
	v_mov_b32_e32 v36, v25
	v_mov_b32_e32 v37, v21
	v_pk_fma_f32 v[34:35], v[34:35], v[34:35], v[38:39]
	s_nop 0
	v_pk_fma_f32 v[34:35], v[36:37], v[36:37], v[34:35]
	s_nop 0
	v_add_f32_e32 v1, v1, v34
	v_add_f32_e32 v1, v1, v35
	ds_bpermute_b32 v32, v42, v1
	s_waitcnt lgkmcnt(0)
	v_add_f32_e32 v1, v1, v32
	ds_bpermute_b32 v32, v43, v1
	s_waitcnt lgkmcnt(0)
	v_add_f32_e32 v1, v1, v32
	ds_bpermute_b32 v32, v44, v1
	s_waitcnt lgkmcnt(0)
	v_add_f32_e32 v1, v1, v32
	ds_bpermute_b32 v32, v45, v1
	s_waitcnt lgkmcnt(0)
	v_add_f32_e32 v1, v1, v32
	ds_bpermute_b32 v32, v46, v1
	s_waitcnt lgkmcnt(0)
	v_add_f32_e32 v1, v1, v32
	ds_bpermute_b32 v32, v47, v1
	s_waitcnt lgkmcnt(0)
	v_add_f32_e32 v1, v1, v32
	v_fmamk_f32 v1, v1, 0x3a800000, v132
	v_cmp_gt_f32_e32 vcc, s9, v1
	v_mul_f32_e32 v32, 0x4b800000, v1
	s_nop 0
	v_cndmask_b32_e32 v1, v1, v32, vcc
	v_rsq_f32_e32 v1, v1
	s_nop 0
	v_mul_f32_e32 v32, 0x45800000, v1
	v_cndmask_b32_e32 v32, v1, v32, vcc
	v_pk_mul_f32 v[14:15], v[14:15], v[32:33] op_sel_hi:[1,0]
	v_pk_mul_f32 v[6:7], v[6:7], v[32:33] op_sel_hi:[1,0]
	v_pk_fma_f32 v[2:3], v[10:11], v[14:15], v[2:3]
	v_pk_mul_f32 v[10:11], v[16:17], v[32:33] op_sel_hi:[1,0]
	v_cvt_pk_bf16_f32 v2, v2, v3
	v_pk_fma_f32 v[4:5], v[12:13], v[10:11], v[4:5]
	s_nop 0
	v_cvt_pk_bf16_f32 v3, v4, v5
	global_store_dwordx2 v[26:27], v[2:3], off
	global_load_dwordx4 v[2:5], v[28:29], off offset:1024
	s_nop 0
	global_load_dwordx4 v[10:13], v[30:31], off offset:1024
	s_waitcnt vmcnt(0)
	v_pk_fma_f32 v[2:3], v[6:7], v[10:11], v[2:3]
	v_pk_mul_f32 v[6:7], v[8:9], v[32:33] op_sel_hi:[1,0]
	v_cvt_pk_bf16_f32 v2, v2, v3
	v_pk_fma_f32 v[4:5], v[6:7], v[12:13], v[4:5]
	v_pk_mul_f32 v[10:11], v[22:23], v[32:33] op_sel_hi:[1,0]
	v_cvt_pk_bf16_f32 v3, v4, v5
	global_store_dwordx2 v[26:27], v[2:3], off offset:512
	global_load_dwordx4 v[2:5], v[28:29], off offset:2048
	s_nop 0
	global_load_dwordx4 v[6:9], v[30:31], off offset:2048
	s_waitcnt vmcnt(0)
	v_pk_fma_f32 v[2:3], v[10:11], v[6:7], v[2:3]
	v_pk_mul_f32 v[6:7], v[24:25], v[32:33] op_sel_hi:[1,0]
	v_cvt_pk_bf16_f32 v2, v2, v3
	v_pk_fma_f32 v[4:5], v[6:7], v[8:9], v[4:5]
	v_pk_mul_f32 v[10:11], v[18:19], v[32:33] op_sel_hi:[1,0]
	v_cvt_pk_bf16_f32 v3, v4, v5
	global_store_dwordx2 v[26:27], v[2:3], off offset:1024
	global_load_dwordx4 v[2:5], v[28:29], off offset:3072
	s_nop 0
	global_load_dwordx4 v[6:9], v[30:31], off offset:3072
	s_waitcnt vmcnt(0)
	v_pk_fma_f32 v[2:3], v[10:11], v[6:7], v[2:3]
	v_pk_mul_f32 v[6:7], v[20:21], v[32:33] op_sel_hi:[1,0]
	v_cvt_pk_bf16_f32 v2, v2, v3
	v_pk_fma_f32 v[4:5], v[6:7], v[8:9], v[4:5]
	s_nop 0
	v_cvt_pk_bf16_f32 v3, v4, v5
	global_store_dwordx2 v[26:27], v[2:3], off offset:1536
	s_cbranch_scc1 .LBB0_27
	s_mov_b64 s[0:1], 0

.LBB0_577:
	v_or_b32_e32 v112, s0, v1
	v_ashrrev_i32_e32 v113, 31, v112
	v_lshlrev_b64 v[114:115], 11, v[112:113]
	v_lshl_add_u64 v[116:117], v[82:83], 0, v[114:115]
	s_movk_i32 s27, 0x4000
	v_readlane_b32 s28, v253, 55
	v_cmp_gt_i32_e32 vcc, s27, v112
	v_add_u32_e32 v114, 0xffffc000, v112
	v_mov_b32_e32 v115, s40
	v_mov_b32_e32 v118, s36
	v_mov_b32_e32 v119, s41
	v_mov_b32_e32 v120, s37
	v_mov_b32_e32 v121, s87
	v_mov_b32_e32 v122, s85
	v_mov_b32_e32 v123, s86
	v_mov_b32_e32 v124, s84
	global_load_dwordx2 v[126:127], v[116:117], off nt
	global_load_dwordx2 v[128:129], v[116:117], off offset:512 nt
	global_load_dwordx2 v[138:139], v[116:117], off offset:1024 nt
	global_load_dwordx2 v[140:141], v[116:117], off offset:1536 nt
	v_readlane_b32 s32, v253, 56
	v_or_b32_e32 v116, 1, v112
	v_cndmask_b32_e32 v117, 0, v113, vcc
	v_cndmask_b32_e32 v125, v114, v112, vcc
	v_cndmask_b32_e32 v114, v115, v118, vcc
	v_cndmask_b32_e32 v134, v119, v120, vcc
	v_cndmask_b32_e32 v137, v121, v122, vcc
	v_cndmask_b32_e32 v142, v123, v124, vcc
	s_mov_b32 s62, s28
	s_mov_b32 s63, s32
	v_lshl_add_u64 v[144:145], v[112:113], 2, s[62:63]
	v_ashrrev_i32_e32 v113, 31, v116
	v_cmp_gt_i32_e32 vcc, s27, v116
	v_add_u32_e32 v143, 0xffffc001, v112
	v_mov_b32_e32 v146, v116
	v_mov_b32_e32 v147, v113
	v_lshlrev_b64 v[148:149], 11, v[146:147]
	v_cndmask_b32_e32 v112, 0, v113, vcc
	v_cndmask_b32_e32 v113, v143, v116, vcc
	v_cndmask_b32_e32 v116, v115, v118, vcc
	v_cndmask_b32_e32 v115, v119, v120, vcc
	v_cndmask_b32_e32 v118, v121, v122, vcc
	v_cndmask_b32_e32 v119, v123, v124, vcc
	v_cndmask_b32_e64 v120, v118, v115, s[2:3]
	v_cndmask_b32_e64 v115, v119, v116, s[2:3]
	v_mov_b32_e32 v118, v113
	v_mov_b32_e32 v119, v112
	v_lshlrev_b64 v[122:123], 12, v[118:119]
	v_cndmask_b32_e64 v112, v137, v134, s[2:3]
	v_cndmask_b32_e64 v113, v142, v114, s[2:3]
	v_mov_b32_e32 v118, v125
	v_mov_b32_e32 v119, v117
	v_lshlrev_b64 v[142:143], 12, v[118:119]
	v_mov_b32_e32 v116, v115
	v_mov_b32_e32 v117, v120
	v_lshl_add_u64 v[118:119], v[116:117], 0, v[122:123]
	s_mov_b32 s27, 0x11000
	v_mov_b32_e32 v114, v113
	v_mov_b32_e32 v115, v112
	v_lshl_add_u64 v[116:117], v[114:115], 0, v[142:143]
	v_lshl_add_u64 v[112:113], v[82:83], 0, v[148:149]
	v_lshl_add_u64 v[114:115], v[118:119], 0, v[130:131]
	v_add_co_u32_e32 v118, vcc, s27, v144
	v_lshl_add_u64 v[120:121], v[116:117], 0, v[130:131]
	global_load_dwordx2 v[116:117], v[112:113], off nt
	global_load_dwordx4 v[122:125], v[114:115], off nt
	global_load_dwordx2 v[142:143], v[112:113], off offset:512 nt
	global_load_dwordx4 v[146:149], v[114:115], off offset:1024 nt
	global_load_dwordx2 v[150:151], v[112:113], off offset:1024 nt
	global_load_dwordx4 v[152:155], v[114:115], off offset:2048 nt
	global_load_dwordx2 v[156:157], v[112:113], off offset:1536 nt
	global_load_dwordx4 v[162:165], v[114:115], off offset:3072 nt
	global_load_dwordx2 v[112:113], v[144:145], off
	v_addc_co_u32_e32 v114, vcc, 0, v145, vcc
	v_mov_b32_e32 v158, v118
	v_mov_b32_e32 v159, v114
	global_load_dwordx2 v[168:169], v[158:159], off
	s_mov_b32 s27, 0x22000
	global_load_dwordx4 v[174:177], v[120:121], off nt
	v_add_co_u32_e32 v114, vcc, s27, v144
	s_mov_b32 s27, 0x33000
	s_nop 0
	v_addc_co_u32_e32 v115, vcc, 0, v145, vcc
	global_load_dwordx2 v[118:119], v[114:115], off
	v_add_co_u32_e32 v114, vcc, s27, v144
	s_mov_b32 s27, 0x44000
	s_nop 0
	v_addc_co_u32_e32 v115, vcc, 0, v145, vcc
	global_load_dwordx2 v[158:159], v[114:115], off
	v_add_co_u32_e32 v114, vcc, s27, v144
	s_mov_b32 s27, 0x55000
	s_nop 0
	v_addc_co_u32_e32 v115, vcc, 0, v145, vcc
	global_load_dwordx2 v[170:171], v[114:115], off
	v_add_co_u32_e32 v114, vcc, s27, v144
	s_mov_b32 s27, 0x66000
	s_nop 0
	v_addc_co_u32_e32 v115, vcc, 0, v145, vcc
	global_load_dwordx2 v[180:181], v[114:115], off
	v_add_co_u32_e32 v114, vcc, s27, v144
	s_mov_b32 s27, 0x77000
	s_nop 0
	v_addc_co_u32_e32 v115, vcc, 0, v145, vcc
	global_load_dwordx2 v[182:183], v[114:115], off
	v_add_co_u32_e32 v114, vcc, s27, v144
	s_mov_b32 s27, 0x88000
	s_nop 0
	v_addc_co_u32_e32 v115, vcc, 0, v145, vcc
	global_load_dwordx2 v[184:185], v[114:115], off
	v_add_co_u32_e32 v114, vcc, s27, v144
	s_mov_b32 s27, 0x99000
	s_nop 0
	v_addc_co_u32_e32 v115, vcc, 0, v145, vcc
	global_load_dwordx2 v[186:187], v[114:115], off
	v_add_co_u32_e32 v114, vcc, s27, v144
	s_mov_b32 s27, 0xaa000
	s_nop 0
	v_addc_co_u32_e32 v115, vcc, 0, v145, vcc
	global_load_dwordx2 v[188:189], v[114:115], off
	v_add_co_u32_e32 v114, vcc, s27, v144
	s_mov_b32 s27, 0xbb000
	s_nop 0
	v_addc_co_u32_e32 v115, vcc, 0, v145, vcc
	global_load_dwordx2 v[190:191], v[114:115], off
	v_add_co_u32_e32 v114, vcc, s27, v144
	s_mov_b32 s27, 0xcc000
	s_nop 0
	v_addc_co_u32_e32 v115, vcc, 0, v145, vcc
	global_load_dwordx2 v[192:193], v[114:115], off
	v_add_co_u32_e32 v114, vcc, s27, v144
	s_mov_b32 s27, 0xdd000
	s_nop 0
	v_addc_co_u32_e32 v115, vcc, 0, v145, vcc
	global_load_dwordx2 v[194:195], v[114:115], off
	v_add_co_u32_e32 v114, vcc, s27, v144
	s_mov_b32 s27, 0xee000
	s_nop 0
	v_addc_co_u32_e32 v115, vcc, 0, v145, vcc
	global_load_dwordx2 v[212:213], v[114:115], off
	v_add_co_u32_e32 v114, vcc, s27, v144
	s_mov_b32 s27, 0xff000
	s_nop 0
	v_addc_co_u32_e32 v115, vcc, 0, v145, vcc
	v_add_co_u32_e32 v134, vcc, s27, v144
	global_load_dwordx2 v[214:215], v[114:115], off
	s_nop 0
	v_addc_co_u32_e32 v114, vcc, 0, v145, vcc
	v_mov_b32_e32 v144, v134
	v_mov_b32_e32 v145, v114
	global_load_dwordx2 v[218:219], v[144:145], off
	global_load_dwordx4 v[220:223], v[120:121], off offset:1024 nt
	global_load_dwordx4 v[224:227], v[120:121], off offset:2048 nt
	global_load_dwordx4 v[228:231], v[120:121], off offset:3072 nt
	v_or_b32_e32 v34, s0, v1
	v_ashrrev_i32_e32 v35, 31, v34
	v_lshlrev_b64 v[88:89], 11, v[34:35]
	v_lshl_add_u64 v[36:37], v[82:83], 0, v[88:89]
	s_movk_i32 s6, 0x4000
	v_readlane_b32 s0, v253, 55
	v_cmp_gt_i32_e32 vcc, s6, v34
	v_add_u32_e32 v38, 0xffffc000, v34
	v_mov_b32_e32 v42, s40
	v_mov_b32_e32 v43, s36
	v_mov_b32_e32 v44, s41
	v_mov_b32_e32 v45, s37
	v_mov_b32_e32 v46, s87
	v_mov_b32_e32 v47, s85
	v_mov_b32_e32 v48, s86
	v_mov_b32_e32 v49, s84
	v_readlane_b32 s1, v253, 56
	v_or_b32_e32 v36, 1, v34
	v_cndmask_b32_e32 v39, 0, v35, vcc
	v_cndmask_b32_e32 v38, v38, v34, vcc
	v_cndmask_b32_e32 v40, v42, v43, vcc
	v_cndmask_b32_e32 v41, v44, v45, vcc
	v_cndmask_b32_e32 v51, v46, v47, vcc
	v_cndmask_b32_e32 v50, v48, v49, vcc
	v_lshl_add_u64 v[58:59], v[34:35], 2, s[0:1]
	v_ashrrev_i32_e32 v37, 31, v36
	v_cmp_gt_i32_e32 vcc, s6, v36
	v_add_u32_e32 v34, 0xffffc001, v34
	v_lshlrev_b64 v[86:87], 11, v[36:37]
	v_cndmask_b32_e32 v35, 0, v37, vcc
	v_cndmask_b32_e32 v34, v34, v36, vcc
	v_cndmask_b32_e32 v36, v42, v43, vcc
	v_cndmask_b32_e32 v37, v44, v45, vcc
	v_cndmask_b32_e32 v97, v46, v47, vcc
	v_cndmask_b32_e32 v96, v48, v49, vcc
	v_cndmask_b32_e64 v37, v97, v37, s[2:3]
	v_cndmask_b32_e64 v36, v96, v36, s[2:3]
	v_lshlrev_b64 v[98:99], 12, v[34:35]
	v_cndmask_b32_e64 v41, v51, v41, s[2:3]
	v_cndmask_b32_e64 v40, v50, v40, s[2:3]
	v_lshlrev_b64 v[54:55], 12, v[38:39]
	v_lshl_add_u64 v[34:35], v[36:37], 0, v[98:99]
	s_mov_b32 s0, 0x11000
	v_lshl_add_u64 v[38:39], v[40:41], 0, v[54:55]
	v_lshl_add_u64 v[64:65], v[82:83], 0, v[86:87]
	v_lshl_add_u64 v[34:35], v[34:35], 0, v[130:131]
	v_add_co_u32_e32 v104, vcc, s0, v58
	v_lshl_add_u64 v[62:63], v[38:39], 0, v[130:131]
	s_waitcnt vmcnt(0)
	v_mov_b32_e32 v92, v116
	v_mov_b32_e32 v93, v117
	v_mov_b32_e32 v38, v122
	v_mov_b32_e32 v39, v123
	v_mov_b32_e32 v40, v124
	v_mov_b32_e32 v41, v125
	v_mov_b32_e32 v100, v142
	v_mov_b32_e32 v101, v143
	v_mov_b32_e32 v46, v146
	v_mov_b32_e32 v47, v147
	v_mov_b32_e32 v48, v148
	v_mov_b32_e32 v49, v149
	v_mov_b32_e32 v94, v150
	v_mov_b32_e32 v95, v151
	v_mov_b32_e32 v42, v152
	v_mov_b32_e32 v43, v153
	v_mov_b32_e32 v44, v154
	v_mov_b32_e32 v45, v155
	v_mov_b32_e32 v90, v156
	v_mov_b32_e32 v91, v157
	s_nop 0
	v_mov_b32_e32 v34, v162
	v_mov_b32_e32 v35, v163
	v_mov_b32_e32 v36, v164
	v_mov_b32_e32 v37, v165
	s_nop 0
	v_addc_co_u32_e32 v105, vcc, 0, v59, vcc
	s_mov_b32 s0, 0x22000
	v_lshl_add_u64 v[50:51], v[50:51], 0, v[54:55]
	v_lshl_add_u64 v[106:107], v[50:51], 0, v[130:131]
	v_lshlrev_b32_e32 v50, 16, v126
	v_and_b32_e32 v51, 0xffff0000, v126
	v_lshlrev_b32_e32 v52, 16, v127
	v_and_b32_e32 v53, 0xffff0000, v127
	v_lshlrev_b32_e32 v54, 16, v128
	v_and_b32_e32 v55, 0xffff0000, v128
	v_lshlrev_b32_e32 v56, 16, v129
	v_and_b32_e32 v57, 0xffff0000, v129
	v_pk_add_f32 v[64:65], v[112:113], 0 op_sel_hi:[1,0]
	v_pk_add_f32 v[64:65], v[64:65], v[168:169]
	v_add_co_u32_e32 v104, vcc, s0, v58
	s_mov_b32 s0, 0x33000
	s_nop 0
	v_addc_co_u32_e32 v105, vcc, 0, v59, vcc
	v_pk_add_f32 v[64:65], v[64:65], v[118:119]
	v_add_co_u32_e32 v104, vcc, s0, v58
	s_mov_b32 s0, 0x44000
	s_nop 0
	v_addc_co_u32_e32 v105, vcc, 0, v59, vcc
	v_pk_add_f32 v[64:65], v[64:65], v[158:159]
	v_add_co_u32_e32 v104, vcc, s0, v58
	s_mov_b32 s0, 0x55000
	s_nop 0
	v_addc_co_u32_e32 v105, vcc, 0, v59, vcc
	v_pk_add_f32 v[64:65], v[64:65], v[170:171]
	v_add_co_u32_e32 v104, vcc, s0, v58
	s_mov_b32 s0, 0x66000
	s_nop 0
	v_addc_co_u32_e32 v105, vcc, 0, v59, vcc
	v_pk_add_f32 v[64:65], v[64:65], v[180:181]
	v_add_co_u32_e32 v104, vcc, s0, v58
	s_mov_b32 s0, 0x77000
	s_nop 0
	v_addc_co_u32_e32 v105, vcc, 0, v59, vcc
	v_pk_add_f32 v[64:65], v[64:65], v[182:183]
	v_add_co_u32_e32 v104, vcc, s0, v58
	s_mov_b32 s0, 0x88000
	s_nop 0
	v_addc_co_u32_e32 v105, vcc, 0, v59, vcc
	v_pk_add_f32 v[64:65], v[64:65], v[184:185]
	v_add_co_u32_e32 v104, vcc, s0, v58
	s_mov_b32 s0, 0x99000
	s_nop 0
	v_addc_co_u32_e32 v105, vcc, 0, v59, vcc
	v_pk_add_f32 v[64:65], v[64:65], v[186:187]
	v_add_co_u32_e32 v104, vcc, s0, v58
	s_mov_b32 s0, 0xaa000
	s_nop 0
	v_addc_co_u32_e32 v105, vcc, 0, v59, vcc
	v_pk_add_f32 v[64:65], v[64:65], v[188:189]
	v_add_co_u32_e32 v104, vcc, s0, v58
	s_mov_b32 s0, 0xbb000
	s_nop 0
	v_addc_co_u32_e32 v105, vcc, 0, v59, vcc
	v_pk_add_f32 v[64:65], v[64:65], v[190:191]
	v_add_co_u32_e32 v104, vcc, s0, v58
	s_mov_b32 s0, 0xcc000
	s_nop 0
	v_addc_co_u32_e32 v105, vcc, 0, v59, vcc
	v_pk_add_f32 v[64:65], v[64:65], v[192:193]
	v_add_co_u32_e32 v104, vcc, s0, v58
	s_mov_b32 s0, 0xdd000
	s_nop 0
	v_addc_co_u32_e32 v105, vcc, 0, v59, vcc
	v_pk_add_f32 v[64:65], v[64:65], v[194:195]
	v_add_co_u32_e32 v104, vcc, s0, v58
	s_mov_b32 s0, 0xee000
	s_nop 0
	v_addc_co_u32_e32 v105, vcc, 0, v59, vcc
	v_pk_add_f32 v[64:65], v[64:65], v[212:213]
	v_add_co_u32_e32 v104, vcc, s0, v58
	s_mov_b32 s0, 0xff000
	s_nop 0
	v_addc_co_u32_e32 v105, vcc, 0, v59, vcc
	v_add_co_u32_e32 v58, vcc, s0, v58
	s_nop 0
	v_addc_co_u32_e32 v59, vcc, 0, v59, vcc
	s_mov_b32 s0, 0x3a800000
	v_pk_add_f32 v[64:65], v[64:65], v[214:215]
	v_pk_add_f32 v[58:59], v[64:65], v[218:219]
	s_nop 0
	v_pk_fma_f32 v[104:105], v[58:59], s[0:1], v[132:133] op_sel_hi:[1,0,0]
	s_mov_b32 s0, 0x800000
	v_mul_f32_e32 v58, 0x4b800000, v104
	v_cmp_gt_f32_e32 vcc, s0, v104
	v_cmp_gt_f32_e64 s[6:7], s0, v105
	s_nop 0
	v_cndmask_b32_e32 v58, v104, v58, vcc
	v_rsq_f32_e32 v58, v58
	s_nop 0
	v_mul_f32_e32 v59, 0x45800000, v58
	v_cndmask_b32_e32 v104, v58, v59, vcc
	v_pk_mul_f32 v[50:51], v[104:105], v[50:51] op_sel_hi:[0,1]
	v_pk_mul_f32 v[52:53], v[104:105], v[52:53] op_sel_hi:[0,1]
	v_pk_fma_f32 v[50:51], v[66:67], v[50:51], v[174:175]
	v_pk_fma_f32 v[52:53], v[68:69], v[52:53], v[176:177]
	v_pk_mul_f32 v[54:55], v[104:105], v[54:55] op_sel_hi:[0,1]
	v_pk_mul_f32 v[56:57], v[104:105], v[56:57] op_sel_hi:[0,1]
	v_lshlrev_b32_e32 v58, 16, v138
	v_and_b32_e32 v59, 0xffff0000, v138
	v_pk_mul_f32 v[58:59], v[104:105], v[58:59] op_sel_hi:[0,1]
	v_lshlrev_b32_e32 v60, 16, v139
	v_and_b32_e32 v61, 0xffff0000, v139
	v_pk_mul_f32 v[60:61], v[104:105], v[60:61] op_sel_hi:[0,1]
	s_and_b64 vcc, exec, s[4:5]
	v_pk_fma_f32 v[54:55], v[70:71], v[54:55], v[220:221]
	v_pk_fma_f32 v[56:57], v[72:73], v[56:57], v[222:223]
	v_mov_b32_e32 v108, v224
	v_mov_b32_e32 v109, v225
	v_mov_b32_e32 v110, v226
	v_mov_b32_e32 v111, v227
	v_pk_fma_f32 v[58:59], v[74:75], v[58:59], v[108:109]
	v_lshlrev_b32_e32 v108, 16, v140
	v_and_b32_e32 v109, 0xffff0000, v140
	v_lshlrev_b32_e32 v102, 16, v141
	v_and_b32_e32 v103, 0xffff0000, v141
	v_pk_mul_f32 v[108:109], v[104:105], v[108:109] op_sel_hi:[0,1]
	v_pk_mul_f32 v[102:103], v[104:105], v[102:103] op_sel_hi:[0,1]
	v_pk_fma_f32 v[60:61], v[76:77], v[60:61], v[110:111]
	global_store_dwordx4 v[106:107], v[50:53], off nt
	global_store_dwordx4 v[106:107], v[54:57], off offset:1024 nt
	global_store_dwordx4 v[106:107], v[58:61], off offset:2048 nt
	v_pk_fma_f32 v[62:63], v[78:79], v[108:109], v[228:229]
	v_pk_fma_f32 v[64:65], v[80:81], v[102:103], v[230:231]
	global_store_dwordx4 v[106:107], v[62:65], off offset:3072 nt
	s_cbranch_vccnz .LBB0_579
	v_mov_b32_e32 v108, v51
	v_mov_b32_e32 v109, v55
	v_mov_b32_e32 v106, v50
	v_mov_b32_e32 v107, v54
	v_pk_mul_f32 v[108:109], v[108:109], v[108:109]
	v_mov_b32_e32 v110, v63
	v_pk_fma_f32 v[106:107], v[106:107], v[106:107], v[108:109]
	v_mov_b32_e32 v108, v52
	v_mov_b32_e32 v109, v56
	v_mov_b32_e32 v111, v59
	v_pk_fma_f32 v[106:107], v[108:109], v[108:109], v[106:107]
	v_mov_b32_e32 v108, v62
	v_mov_b32_e32 v109, v58
	v_pk_mul_f32 v[110:111], v[110:111], v[110:111]
	v_mov_b32_e32 v102, v53
	v_mov_b32_e32 v103, v57
	v_pk_fma_f32 v[108:109], v[108:109], v[108:109], v[110:111]
	v_mov_b32_e32 v110, v64
	v_mov_b32_e32 v111, v60
	v_pk_fma_f32 v[102:103], v[102:103], v[102:103], v[106:107]
	v_mov_b32_e32 v106, v65
	v_mov_b32_e32 v107, v61
	v_pk_fma_f32 v[108:109], v[110:111], v[110:111], v[108:109]
	v_add_f32_e32 v102, v102, v103
	v_pk_fma_f32 v[106:107], v[106:107], v[106:107], v[108:109]
	v_cmp_lt_i32_e32 vcc, v201, v200
	v_add_f32_e32 v102, v107, v102
	v_add_f32_e32 v102, v106, v102
	v_cndmask_b32_e32 v103, v198, v201, vcc
	v_lshlrev_b32_e32 v103, 2, v103
	ds_bpermute_b32 v103, v103, v102
	v_cmp_lt_i32_e32 vcc, v202, v200
	v_lshl_add_u64 v[88:89], v[84:85], 0, v[88:89]
	s_waitcnt lgkmcnt(0)
	v_add_f32_e32 v102, v102, v103
	v_cndmask_b32_e32 v103, v198, v202, vcc
	v_lshlrev_b32_e32 v103, 2, v103
	ds_bpermute_b32 v103, v103, v102
	v_cmp_lt_i32_e32 vcc, v203, v200
	s_waitcnt lgkmcnt(0)
	v_add_f32_e32 v102, v102, v103
	v_cndmask_b32_e32 v103, v198, v203, vcc
	v_lshlrev_b32_e32 v103, 2, v103
	ds_bpermute_b32 v103, v103, v102
	v_cmp_lt_i32_e32 vcc, v204, v200
	s_waitcnt lgkmcnt(0)
	v_add_f32_e32 v102, v102, v103
	v_cndmask_b32_e32 v103, v198, v204, vcc
	v_lshlrev_b32_e32 v103, 2, v103
	ds_bpermute_b32 v103, v103, v102
	v_cmp_lt_i32_e32 vcc, v205, v200
	s_waitcnt lgkmcnt(0)
	v_add_f32_e32 v102, v102, v103
	v_cndmask_b32_e32 v103, v198, v205, vcc
	v_lshlrev_b32_e32 v103, 2, v103
	ds_bpermute_b32 v103, v103, v102
	v_cmp_lt_i32_e32 vcc, v206, v200
	s_waitcnt lgkmcnt(0)
	v_add_f32_e32 v102, v102, v103
	v_cndmask_b32_e32 v103, v198, v206, vcc
	v_lshlrev_b32_e32 v103, 2, v103
	ds_bpermute_b32 v103, v103, v102
	s_waitcnt lgkmcnt(0)
	v_add_f32_e32 v102, v102, v103
	v_fmamk_f32 v102, v102, 0x3a800000, v132
	v_mul_f32_e32 v103, 0x4b800000, v102
	v_cmp_gt_f32_e32 vcc, s0, v102
	s_nop 1
	v_cndmask_b32_e32 v102, v102, v103, vcc
	v_rsq_f32_e32 v102, v102
	s_nop 0
	v_mul_f32_e32 v103, 0x45800000, v102
	v_cndmask_b32_e32 v102, v102, v103, vcc
	v_pk_mul_f32 v[50:51], v[50:51], v[102:103] op_sel_hi:[1,0]
	v_pk_mul_f32 v[52:53], v[52:53], v[102:103] op_sel_hi:[1,0]
	v_pk_fma_f32 v[50:51], v[6:7], v[50:51], v[2:3]
	v_pk_fma_f32 v[52:53], v[8:9], v[52:53], v[4:5]
	v_cvt_pk_bf16_f32 v50, v50, v51
	v_cvt_pk_bf16_f32 v51, v52, v53
	global_store_dwordx2 v[88:89], v[50:51], off
	v_pk_mul_f32 v[50:51], v[54:55], v[102:103] op_sel_hi:[1,0]
	v_pk_mul_f32 v[52:53], v[56:57], v[102:103] op_sel_hi:[1,0]
	v_pk_fma_f32 v[50:51], v[14:15], v[50:51], v[10:11]
	v_pk_fma_f32 v[52:53], v[16:17], v[52:53], v[12:13]
	v_cvt_pk_bf16_f32 v50, v50, v51
	v_cvt_pk_bf16_f32 v51, v52, v53
	global_store_dwordx2 v[88:89], v[50:51], off offset:512
	v_pk_mul_f32 v[50:51], v[58:59], v[102:103] op_sel_hi:[1,0]
	v_pk_mul_f32 v[52:53], v[60:61], v[102:103] op_sel_hi:[1,0]
	v_pk_fma_f32 v[50:51], v[22:23], v[50:51], v[18:19]
	v_pk_fma_f32 v[52:53], v[24:25], v[52:53], v[20:21]
	v_cvt_pk_bf16_f32 v50, v50, v51
	v_cvt_pk_bf16_f32 v51, v52, v53
	global_store_dwordx2 v[88:89], v[50:51], off offset:1024
	v_pk_mul_f32 v[50:51], v[62:63], v[102:103] op_sel_hi:[1,0]
	v_pk_mul_f32 v[52:53], v[64:65], v[102:103] op_sel_hi:[1,0]
	v_pk_fma_f32 v[50:51], v[30:31], v[50:51], v[26:27]
	v_pk_fma_f32 v[52:53], v[32:33], v[52:53], v[28:29]
	v_cvt_pk_bf16_f32 v50, v50, v51
	v_cvt_pk_bf16_f32 v51, v52, v53
	global_store_dwordx2 v[88:89], v[50:51], off offset:1536
.LBB0_579:
	v_mul_f32_e32 v50, 0x4b800000, v105
	v_cndmask_b32_e64 v50, v105, v50, s[6:7]
	v_rsq_f32_e32 v53, v50
	v_lshlrev_b32_e32 v52, 16, v92
	v_lshl_add_u64 v[50:51], v[96:97], 0, v[98:99]
	v_lshl_add_u64 v[50:51], v[50:51], 0, v[130:131]
	v_mul_f32_e32 v54, 0x45800000, v53
	v_cndmask_b32_e64 v54, v53, v54, s[6:7]
	v_and_b32_e32 v53, 0xffff0000, v92
	v_pk_mul_f32 v[52:53], v[54:55], v[52:53] op_sel_hi:[0,1]
	v_pk_fma_f32 v[38:39], v[66:67], v[52:53], v[38:39]
	v_lshlrev_b32_e32 v52, 16, v93
	v_and_b32_e32 v53, 0xffff0000, v93
	v_pk_mul_f32 v[52:53], v[54:55], v[52:53] op_sel_hi:[0,1]
	v_pk_fma_f32 v[40:41], v[68:69], v[52:53], v[40:41]
	v_lshlrev_b32_e32 v52, 16, v100
	v_and_b32_e32 v53, 0xffff0000, v100
	v_pk_mul_f32 v[52:53], v[54:55], v[52:53] op_sel_hi:[0,1]
	v_pk_fma_f32 v[46:47], v[70:71], v[52:53], v[46:47]
	v_lshlrev_b32_e32 v52, 16, v101
	v_and_b32_e32 v53, 0xffff0000, v101
	v_pk_mul_f32 v[52:53], v[54:55], v[52:53] op_sel_hi:[0,1]
	v_pk_fma_f32 v[48:49], v[72:73], v[52:53], v[48:49]
	v_lshlrev_b32_e32 v52, 16, v94
	v_and_b32_e32 v53, 0xffff0000, v94
	v_pk_mul_f32 v[52:53], v[54:55], v[52:53] op_sel_hi:[0,1]
	v_pk_fma_f32 v[42:43], v[74:75], v[52:53], v[42:43]
	v_lshlrev_b32_e32 v52, 16, v95
	v_and_b32_e32 v53, 0xffff0000, v95
	v_pk_mul_f32 v[52:53], v[54:55], v[52:53] op_sel_hi:[0,1]
	v_pk_fma_f32 v[44:45], v[76:77], v[52:53], v[44:45]
	v_lshlrev_b32_e32 v52, 16, v90
	v_and_b32_e32 v53, 0xffff0000, v90
	v_pk_mul_f32 v[52:53], v[54:55], v[52:53] op_sel_hi:[0,1]
	v_pk_fma_f32 v[34:35], v[78:79], v[52:53], v[34:35]
	v_lshlrev_b32_e32 v52, 16, v91
	v_and_b32_e32 v53, 0xffff0000, v91
	v_pk_mul_f32 v[52:53], v[54:55], v[52:53] op_sel_hi:[0,1]
	v_pk_fma_f32 v[36:37], v[80:81], v[52:53], v[36:37]
	s_and_b64 vcc, exec, s[4:5]
	global_store_dwordx4 v[50:51], v[38:41], off nt
	global_store_dwordx4 v[50:51], v[46:49], off offset:1024 nt
	global_store_dwordx4 v[50:51], v[42:45], off offset:2048 nt
	global_store_dwordx4 v[50:51], v[34:37], off offset:3072 nt
	s_cbranch_vccnz .LBB0_576
	v_mov_b32_e32 v54, v39
	v_mov_b32_e32 v55, v47
	v_mov_b32_e32 v52, v38
	v_mov_b32_e32 v53, v46
	v_pk_mul_f32 v[54:55], v[54:55], v[54:55]
	v_mov_b32_e32 v56, v35
	v_pk_fma_f32 v[52:53], v[52:53], v[52:53], v[54:55]
	v_mov_b32_e32 v54, v40
	v_mov_b32_e32 v55, v48
	v_mov_b32_e32 v57, v43
	v_pk_fma_f32 v[52:53], v[54:55], v[54:55], v[52:53]
	v_mov_b32_e32 v54, v34
	v_mov_b32_e32 v55, v42
	v_pk_mul_f32 v[56:57], v[56:57], v[56:57]
	v_mov_b32_e32 v50, v41
	v_mov_b32_e32 v51, v49
	v_pk_fma_f32 v[54:55], v[54:55], v[54:55], v[56:57]
	v_mov_b32_e32 v56, v36
	v_mov_b32_e32 v57, v44
	v_pk_fma_f32 v[50:51], v[50:51], v[50:51], v[52:53]
	v_mov_b32_e32 v52, v37
	v_mov_b32_e32 v53, v45
	v_pk_fma_f32 v[54:55], v[56:57], v[56:57], v[54:55]
	v_add_f32_e32 v50, v50, v51
	v_pk_fma_f32 v[52:53], v[52:53], v[52:53], v[54:55]
	v_cmp_lt_i32_e32 vcc, v201, v200
	v_add_f32_e32 v50, v53, v50
	v_add_f32_e32 v50, v52, v50
	v_cndmask_b32_e32 v51, v198, v201, vcc
	v_lshlrev_b32_e32 v51, 2, v51
	ds_bpermute_b32 v51, v51, v50
	v_cmp_lt_i32_e32 vcc, v202, v200
	v_lshl_add_u64 v[52:53], v[84:85], 0, v[86:87]
	s_waitcnt lgkmcnt(0)
	v_add_f32_e32 v50, v50, v51
	v_cndmask_b32_e32 v51, v198, v202, vcc
	v_lshlrev_b32_e32 v51, 2, v51
	ds_bpermute_b32 v51, v51, v50
	v_cmp_lt_i32_e32 vcc, v203, v200
	s_waitcnt lgkmcnt(0)
	v_add_f32_e32 v50, v50, v51
	v_cndmask_b32_e32 v51, v198, v203, vcc
	v_lshlrev_b32_e32 v51, 2, v51
	ds_bpermute_b32 v51, v51, v50
	v_cmp_lt_i32_e32 vcc, v204, v200
	s_waitcnt lgkmcnt(0)
	v_add_f32_e32 v50, v50, v51
	v_cndmask_b32_e32 v51, v198, v204, vcc
	v_lshlrev_b32_e32 v51, 2, v51
	ds_bpermute_b32 v51, v51, v50
	v_cmp_lt_i32_e32 vcc, v205, v200
	s_waitcnt lgkmcnt(0)
	v_add_f32_e32 v50, v50, v51
	v_cndmask_b32_e32 v51, v198, v205, vcc
	v_lshlrev_b32_e32 v51, 2, v51
	ds_bpermute_b32 v51, v51, v50
	v_cmp_lt_i32_e32 vcc, v206, v200
	s_waitcnt lgkmcnt(0)
	v_add_f32_e32 v50, v50, v51
	v_cndmask_b32_e32 v51, v198, v206, vcc
	v_lshlrev_b32_e32 v51, 2, v51
	ds_bpermute_b32 v51, v51, v50
	s_waitcnt lgkmcnt(0)
	v_add_f32_e32 v50, v50, v51
	v_fmamk_f32 v50, v50, 0x3a800000, v132
	v_mul_f32_e32 v51, 0x4b800000, v50
	v_cmp_gt_f32_e32 vcc, s0, v50
	s_nop 1
	v_cndmask_b32_e32 v50, v50, v51, vcc
	v_rsq_f32_e32 v50, v50
	s_nop 0
	v_mul_f32_e32 v51, 0x45800000, v50
	v_cndmask_b32_e32 v50, v50, v51, vcc
	v_pk_mul_f32 v[38:39], v[38:39], v[50:51] op_sel_hi:[1,0]
	v_pk_mul_f32 v[40:41], v[40:41], v[50:51] op_sel_hi:[1,0]
	v_pk_fma_f32 v[38:39], v[6:7], v[38:39], v[2:3]
	v_pk_fma_f32 v[40:41], v[8:9], v[40:41], v[4:5]
	v_cvt_pk_bf16_f32 v38, v38, v39
	v_cvt_pk_bf16_f32 v39, v40, v41
	global_store_dwordx2 v[52:53], v[38:39], off
	v_pk_mul_f32 v[38:39], v[46:47], v[50:51] op_sel_hi:[1,0]
	v_pk_mul_f32 v[40:41], v[48:49], v[50:51] op_sel_hi:[1,0]
	v_pk_fma_f32 v[38:39], v[14:15], v[38:39], v[10:11]
	v_pk_fma_f32 v[40:41], v[16:17], v[40:41], v[12:13]
	v_cvt_pk_bf16_f32 v38, v38, v39
	v_cvt_pk_bf16_f32 v39, v40, v41
	global_store_dwordx2 v[52:53], v[38:39], off offset:512
	v_pk_mul_f32 v[38:39], v[42:43], v[50:51] op_sel_hi:[1,0]
	v_pk_mul_f32 v[40:41], v[44:45], v[50:51] op_sel_hi:[1,0]
	v_pk_mul_f32 v[34:35], v[34:35], v[50:51] op_sel_hi:[1,0]
	v_pk_mul_f32 v[36:37], v[36:37], v[50:51] op_sel_hi:[1,0]
	v_pk_fma_f32 v[38:39], v[22:23], v[38:39], v[18:19]
	v_pk_fma_f32 v[40:41], v[24:25], v[40:41], v[20:21]
	v_pk_fma_f32 v[34:35], v[30:31], v[34:35], v[26:27]
	v_pk_fma_f32 v[36:37], v[32:33], v[36:37], v[28:29]
	v_cvt_pk_bf16_f32 v38, v38, v39
	v_cvt_pk_bf16_f32 v39, v40, v41
	v_cvt_pk_bf16_f32 v34, v34, v35
	v_cvt_pk_bf16_f32 v35, v36, v37
	global_store_dwordx2 v[52:53], v[38:39], off offset:1024
	global_store_dwordx2 v[52:53], v[34:35], off offset:1536
	s_branch .LBB0_576
